# two-phase dilated attention: branches g0,g1 before grid sync, g2 rounds with fused branch merge (separate merge pass removed)
# baseline (speedup 1.0000x reference)
; #define PHASE_IDS() int tid = tid0; asm volatile("" : "+v"(tid)); const int lane = tid & 63, wave = __builtin_amdgcn_readfirstlane(tid >> 6), gw = bx * 8 + wave; (void)lane; (void)gw;
; __device__ __forceinline__ void phase(LAS unsigned char* L, const u16* __restrict__ QKV, u16* OBg0, u16* OBg1, u16* OBg2, float* LSE, int first, int stride, const int tid) {
;     ...
;     const bool xl = (stride == 256); const int nround = xl ? 24 : (6144 - first + stride - 1) / stride;
;     if (first >= 6144) return;
;     ...
;     v4u pk[6], pv[6]; bf16x8 qn[4];
;     issue(QKV, DL_TASK(0), tid, pk, pv, qn);
; __global__ void __launch_bounds__(512, 2) fwd_kernel(Args A) {
;     ...
;             for (int rep_ = 0; rep_ < REP_DIL; ++rep_) { { PHASE_IDS(); dl::phase(lds, HB, AUX, OB1, XB, LSE, vcu, G, tid); } }
.LBB0_466:
	v_readlane_b32 s0, v253, 25
	v_readlane_b32 s2, v255, 24
	s_barrier
	v_mbcnt_lo_u32_b32 v0, -1, 0
	v_mbcnt_hi_u32_b32 v0, -1, v0
	v_readlane_b32 s3, v255, 25
	v_add_u32_e32 v3, s0, v0
	s_mov_b32 s6, 16
	v_readfirstlane_b32 s0, v3
	s_and_b64 vcc, exec, s[2:3]
	s_cbranch_vccz .LBB0_468
	v_readlane_b32 s6, v255, 38

; #define LAS __attribute__((address_space(3)))
; __device__ __forceinline__ void phase(LAS unsigned char* L, const u16* __restrict__ QKV, u16* OBg0, u16* OBg1, u16* OBg2, float* LSE, int first, int stride, const int tid) {
;     ...
;     for (int kr = 0; kr < nround; ++kr) {
;         const int task = DL_TASK(kr);
;         const Dec d = decode(task);
; #pragma unroll
;         for (int n = 0; n < 6; ++n) { const int id = tid + 512 * n, c = id >> 3, ch = id & 7; *(LAS v4u*)(L + O_K + c * KP + ch * 16) = pk[n]; *(LAS v4u*)(L + O_V + c * VP + ch * 16) = pv[n]; }
;         bf16x8 qf[4];
; #pragma unroll
;         for (int ks = 0; ks < 4; ++ks) qf[ks] = qn[ks];
;         __syncthreads();
;         if (kr + 1 < nround) issue(QKV, DL_TASK(kr + 1), tid, pk, pv, qn);
;     ...
;         __syncthreads();
.LBB0_471:
	s_or_b64 exec, exec, vcc
	s_add_i32 s10, s10, s32
	s_waitcnt vmcnt(4)
	v_mov_b64_e32 v[148:149], v[144:145]
	v_mov_b64_e32 v[152:153], v[140:141]
	v_mov_b64_e32 v[156:157], v[136:137]
	v_mov_b64_e32 v[66:67], v[130:131]
	s_cmp_lg_u32 s6, s93
	v_mov_b64_e32 v[146:147], v[142:143]
	v_mov_b64_e32 v[150:151], v[138:139]
	v_mov_b64_e32 v[154:155], v[134:135]
	v_mov_b64_e32 v[68:69], v[132:133]
	s_mov_b64 s[50:51], s[74:75]
	s_barrier
	s_cbranch_scc0 .LBB0_484

; #define LAS __attribute__((address_space(3)))
; __device__ __forceinline__ void phase(LAS unsigned char* L, const u16* __restrict__ QKV, u16* OBg0, u16* OBg1, u16* OBg2, float* LSE, int first, int stride, const int tid) {
;     ...
;     for (int kr = 0; kr < nround; ++kr) {
;         const int task = DL_TASK(kr);
;         const Dec d = decode(task);
; #pragma unroll
;         for (int n = 0; n < 6; ++n) { const int id = tid + 512 * n, c = id >> 3, ch = id & 7; *(LAS v4u*)(L + O_K + c * KP + ch * 16) = pk[n]; *(LAS v4u*)(L + O_V + c * VP + ch * 16) = pv[n]; }
;         bf16x8 qf[4];
; #pragma unroll
;         for (int ks = 0; ks < 4; ++ks) qf[ks] = qn[ks];
;         __syncthreads();
;         if (kr + 1 < nround) issue(QKV, DL_TASK(kr + 1), tid, pk, pv, qn);
.LBB0_474:
	s_add_i32 s93, s93, 1
	s_and_b32 s32, s93, 1
	s_lshl_b32 s32, s32, 5
	s_sub_i32 s32, 64, s32
	s_waitcnt vmcnt(12)
	v_mov_b64_e32 v[132:133], v[68:69]
	v_mov_b64_e32 v[134:135], v[154:155]
	v_mov_b64_e32 v[138:139], v[150:151]
	v_mov_b64_e32 v[142:143], v[146:147]
	s_cmp_ge_i32 s93, s6
	v_mov_b64_e32 v[130:131], v[66:67]
	v_mov_b64_e32 v[136:137], v[156:157]
	v_mov_b64_e32 v[140:141], v[152:153]
	v_mov_b64_e32 v[144:145], v[148:149]
	s_waitcnt vmcnt(0)
	ds_write_b128 v203, v[114:117]
	ds_write_b128 v208, v[122:125] offset:55296
	ds_write_b128 v209, v[118:121]
	ds_write_b128 v210, v[126:129] offset:55296
	ds_write_b128 v211, v[98:101]
	ds_write_b128 v212, v[106:109] offset:55296
	ds_write_b128 v213, v[102:105]
	ds_write_b128 v214, v[110:113] offset:55296
	ds_write_b128 v215, v[82:85]
	ds_write_b128 v216, v[90:93] offset:55296
	ds_write_b128 v217, v[86:89]
	ds_write_b128 v218, v[94:97] offset:55296
	s_waitcnt lgkmcnt(0)
	s_barrier
	s_cbranch_scc1 .LBB0_480
	v_readlane_b32 s12, v255, 24
	v_readlane_b32 s13, v255, 25
	s_mov_b32 s8, s6
	s_mov_b64 s[6:7], s[2:3]
	s_mov_b64 s[2:3], s[64:65]
	s_mov_b64 s[64:65], s[62:63]
	s_mov_b64 s[62:63], s[60:61]
	s_mov_b64 s[60:61], s[58:59]
	s_mov_b64 s[58:59], s[56:57]
	s_mov_b64 s[56:57], s[54:55]
	s_mov_b64 s[54:55], s[52:53]
	s_mov_b64 s[52:53], s[4:5]
	s_mov_b64 s[4:5], s[48:49]
	s_mov_b64 s[48:49], s[46:47]
	s_mov_b64 s[46:47], s[44:45]
	s_mov_b64 s[44:45], s[42:43]
	s_mov_b64 s[42:43], s[40:41]
	s_mov_b64 s[40:41], s[38:39]
	s_mov_b64 s[38:39], s[36:37]
	s_mov_b64 s[36:37], s[34:35]
	s_mov_b64 s[34:35], s[30:31]
	s_mov_b64 s[30:31], s[28:29]
	s_mov_b64 s[28:29], s[26:27]
	s_mov_b64 s[26:27], s[24:25]
	s_mov_b64 s[24:25], s[22:23]
	s_mov_b64 s[22:23], s[20:21]
	s_mov_b64 s[20:21], s[18:19]
	s_mov_b64 s[18:19], s[16:17]
	s_mov_b64 s[16:17], s[88:89]
	s_mov_b64 s[88:89], s[76:77]
	s_mov_b64 s[76:77], s[50:51]
	s_mov_b64 s[0:1], -1
	s_and_b64 vcc, exec, s[12:13]
	s_cbranch_vccz .LBB0_477
	v_readlane_b32 s0, v255, 58
	s_mul_i32 s0, s93, s0
	v_readlane_b32 s1, v253, 8
	s_add_i32 s11, s0, s1
	s_mov_b64 s[0:1], 0
.LBB0_477:
	v_readlane_b32 s12, v254, 12
	s_andn2_b64 vcc, exec, s[0:1]
	v_readlane_b32 s13, v254, 13
	s_cbranch_vccnz .LBB0_479
	s_add_i32 s11, s10, s32

; #define LAS __attribute__((address_space(3)))
; __device__ __forceinline__ void issue(const u16* __restrict__ QKV, int task, int tid, v4u (&pk)[6], v4u (&pv)[6], bf16x8 (&qn)[4]) {
;     const Dec d = decode(task); const int lane = tid & 63, w = tid >> 6, r = lane & 31, h = lane >> 5;
; #pragma unroll
;     for (int n = 0; n < 6; ++n) { const int id = tid + 512 * n, c = id >> 3, ch = id & 7; int ki = d.i0 - 128 + c; ki = ki < 0 ? 0 : ki;
;     ...
;         pk[n] = *(const v4u*)(src + 1024); pv[n] = *(const v4u*)(src + 2048); }
;     ...
; #pragma unroll
;     for (int ks = 0; ks < 4; ++ks) qn[ks] = *(const bf16x8*)(qp + 16 * ks + 8 * h);
; }
; __device__ __forceinline__ void phase(LAS unsigned char* L, const u16* __restrict__ QKV, u16* OBg0, u16* OBg1, u16* OBg2, float* LSE, int first, int stride, const int tid) {
;     const int lane = tid & 63, w = __builtin_amdgcn_readfirstlane(tid >> 6), r = lane & 31, h = lane >> 5;
;     const bool xl = (stride == 256); const int nround = xl ? 24 : (6144 - first + stride - 1) / stride;
;     if (first >= 6144) return;
;     ...
;     v4u pk[6], pv[6]; bf16x8 qn[4];
;     issue(QKV, DL_TASK(0), tid, pk, pv, qn);
.LBB0_507:
	s_barrier
	v_readlane_b32 s0, v253, 25
	v_readlane_b32 s2, v255, 24
	v_mbcnt_lo_u32_b32 v0, -1, 0
	v_mbcnt_hi_u32_b32 v0, -1, v0
	v_readlane_b32 s3, v255, 25
	v_add_u32_e32 v3, s0, v0
	s_mov_b32 s6, 8
	v_readfirstlane_b32 s0, v3
	s_and_b64 vcc, exec, s[2:3]
	s_cbranch_vccz .Ldb_468
	v_readlane_b32 s6, v255, 38
.Ldb_468:
	v_readlane_b32 s2, v255, 26
	v_readlane_b32 s3, v255, 27
	s_andn2_b64 vcc, exec, s[2:3]
	s_cbranch_vccnz .LBB0_510
	s_cmp_lt_i32 s6, 1
	s_cbranch_scc1 .LBB0_510
	v_ashrrev_i32_e32 v4, 1, v3
	v_and_b32_e32 v5, 0xffffffe0, v4
	s_movk_i32 s11, 0xffe0
	v_readlane_b32 s1, v255, 36
	s_lshr_b32 s98, s1, 8
	s_and_b32 s1, s98, 1
	s_lshl_b32 s1, s1, 8
	s_add_i32 s99, s1, 0xffffff80
	s_lshr_b32 s98, s98, 1
	v_and_b32_e32 v162, 31, v3
	v_bfi_b32 v169, s11, v4, v3
	v_add_u32_e32 v4, s1, v5
	v_add_u32_e32 v0, 0x200, v3
	v_or_b32_e32 v4, v4, v162
	s_mov_b32 s1, 4
	v_ashrrev_i32_e32 v164, 3, v0
	v_add_u32_e32 v0, 0x400, v3
	v_lshlrev_b32_e32 v4, s1, v4
	v_readlane_b32 s4, v255, 31
	v_readlane_b32 s8, v255, 34
	v_ashrrev_i32_e32 v165, 3, v0
	v_add_u32_e32 v0, 0x600, v3
	v_ashrrev_i32_e32 v5, 31, v4
	v_readlane_b32 s5, v255, 32
	s_or_b32 s4, s4, s98
	v_readlane_b32 s9, v255, 35
	v_ashrrev_i32_e32 v166, 3, v0
	v_add_u32_e32 v0, 0x800, v3
	v_lshl_add_u64 v[4:5], s[4:5], 0, v[4:5]
	v_mov_b64_e32 v[6:7], s[8:9]
	s_movk_i32 s10, 0x1800
	v_ashrrev_i32_e32 v167, 3, v0
	v_add_u32_e32 v0, 0xa00, v3
	v_mad_u64_u32 v[6:7], s[2:3], v4, s10, v[6:7]
	v_ashrrev_i32_e32 v168, 3, v0
	v_lshrrev_b32_e32 v0, 2, v3
	v_mov_b32_e32 v4, v7
	v_and_b32_e32 v2, 8, v0
	v_mad_u64_u32 v[4:5], s[2:3], v5, s10, v[4:5]
	v_lshlrev_b32_e32 v0, 4, v3
	v_mov_b32_e32 v7, v4
	v_lshlrev_b32_e32 v4, 1, v2
	v_mov_b32_e32 v5, v1
	v_and_b32_e32 v0, 0x70, v0
	v_lshl_add_u64 v[4:5], v[6:7], 0, v[4:5]
	global_load_dwordx4 v[146:149], v[4:5], off offset:96
	global_load_dwordx4 v[150:153], v[4:5], off offset:64
	global_load_dwordx4 v[154:157], v[4:5], off offset:32
	global_load_dwordx4 v[66:69], v[4:5], off
	v_lshl_add_u64 v[4:5], s[8:9], 0, v[0:1]
	s_mov_b32 s8, s99
	s_movk_i32 s9, 0x1000
	v_ashrrev_i32_e32 v163, 3, v3
	v_add_u32_e32 v6, s8, v168
	v_max_i32_e32 v6, 0, v6
	v_lshlrev_b32_e32 v6, s1, v6
	v_ashrrev_i32_e32 v7, 31, v6
	v_lshl_add_u64 v[6:7], s[4:5], 0, v[6:7]
	v_mad_u64_u32 v[8:9], s[2:3], v6, s10, v[4:5]
	v_mov_b32_e32 v6, v9
	v_mad_u64_u32 v[6:7], s[2:3], v7, s10, v[6:7]
	v_add_co_u32_e32 v10, vcc, s9, v8
	v_mov_b32_e32 v9, v6
	s_nop 0
	v_addc_co_u32_e32 v11, vcc, 0, v6, vcc
	v_add_u32_e32 v6, s8, v167
	v_max_i32_e32 v6, 0, v6
	v_lshlrev_b32_e32 v6, s1, v6
	v_ashrrev_i32_e32 v7, 31, v6
	v_lshl_add_u64 v[6:7], s[4:5], 0, v[6:7]
	v_mad_u64_u32 v[12:13], s[2:3], v6, s10, v[4:5]
	v_mov_b32_e32 v6, v13
	v_mad_u64_u32 v[6:7], s[2:3], v7, s10, v[6:7]
	v_add_co_u32_e32 v14, vcc, s9, v12
	v_mov_b32_e32 v13, v6
	s_nop 0
	v_addc_co_u32_e32 v15, vcc, 0, v6, vcc
	v_add_u32_e32 v6, s8, v166
	v_max_i32_e32 v6, 0, v6
	v_lshlrev_b32_e32 v6, s1, v6
	v_ashrrev_i32_e32 v7, 31, v6
	v_lshl_add_u64 v[6:7], s[4:5], 0, v[6:7]
	global_load_dwordx4 v[94:97], v[10:11], off
	global_load_dwordx4 v[90:93], v[14:15], off
	global_load_dwordx4 v[86:89], v[8:9], off offset:2048
	global_load_dwordx4 v[82:85], v[12:13], off offset:2048
	v_mad_u64_u32 v[8:9], s[2:3], v6, s10, v[4:5]
	v_mov_b32_e32 v6, v9
	v_mad_u64_u32 v[6:7], s[2:3], v7, s10, v[6:7]
	v_add_co_u32_e32 v10, vcc, s9, v8
	v_mov_b32_e32 v9, v6
	s_nop 0
	v_addc_co_u32_e32 v11, vcc, 0, v6, vcc
	v_add_u32_e32 v6, s8, v165
	v_max_i32_e32 v6, 0, v6
	v_lshlrev_b32_e32 v6, s1, v6
	v_ashrrev_i32_e32 v7, 31, v6
	v_lshl_add_u64 v[6:7], s[4:5], 0, v[6:7]
	v_mad_u64_u32 v[12:13], s[2:3], v6, s10, v[4:5]
	v_mov_b32_e32 v6, v13
	v_mad_u64_u32 v[6:7], s[2:3], v7, s10, v[6:7]
	v_add_co_u32_e32 v14, vcc, s9, v12
	v_mov_b32_e32 v13, v6
	s_nop 0
	v_addc_co_u32_e32 v15, vcc, 0, v6, vcc
	v_add_u32_e32 v6, s8, v164
	v_max_i32_e32 v6, 0, v6
	v_lshlrev_b32_e32 v6, s1, v6
	v_ashrrev_i32_e32 v7, 31, v6
	v_lshl_add_u64 v[6:7], s[4:5], 0, v[6:7]
	global_load_dwordx4 v[110:113], v[10:11], off
	global_load_dwordx4 v[106:109], v[14:15], off
	global_load_dwordx4 v[102:105], v[8:9], off offset:2048
	global_load_dwordx4 v[98:101], v[12:13], off offset:2048
	v_mad_u64_u32 v[8:9], s[2:3], v6, s10, v[4:5]
	v_mov_b32_e32 v6, v9
	v_mad_u64_u32 v[6:7], s[2:3], v7, s10, v[6:7]
	v_add_co_u32_e32 v10, vcc, s9, v8
	v_mov_b32_e32 v9, v6
	s_nop 0
	v_addc_co_u32_e32 v11, vcc, 0, v6, vcc
	v_add_u32_e32 v6, s8, v163
	v_max_i32_e32 v6, 0, v6
	v_lshlrev_b32_e32 v6, s1, v6
; __device__ __forceinline__ int crow(int r,int hi){return (r&3)+8*(r>>2)+4*hi;}
; #define LAS __attribute__((address_space(3)))
; __device__ __forceinline__ int crow(int reg, int h) { return (reg & 3) + 8 * (reg >> 2) + 4 * h; }
; #define MFMA32(a, b, c) __builtin_amdgcn_mfma_f32_32x32x16_bf16((a), (b), (c), 0, 0, 0)
; __device__ __forceinline__ void phase(LAS unsigned char* L, const u16* __restrict__ QKV, u16* OBg0, u16* OBg1, u16* OBg2, float* LSE, int first, int stride, const int tid) {
;     ...
;         const int qpos = d.res + ((i0 + 32 * w + r) << sh);
;         f32x16 X[5];
; #pragma unroll
;         for (int kb = 0; kb < 5; ++kb) X[kb] = f32x16{};
;         {
;             LAS unsigned char* kbase = L + O_K + (32 * w + r) * KP + 8 * h * 2;
; #pragma unroll
;             for (int ks = 0; ks < 4; ++ks) {
;                 bf16x8 kf[5];
; #pragma unroll
;                 for (int kb = 0; kb < 5; ++kb) kf[kb] = *(LAS bf16x8*)(kbase + 32 * kb * KP + 16 * ks * 2);
; #pragma unroll
;                 for (int kb = 0; kb < 5; ++kb) X[kb] = MFMA32(kf[kb], qf[ks], X[kb]);
;             }
;         }
;         float m = -INFINITY;
;         const int kneg = 128 - i0 - 32 * w;
; #pragma unroll
;         for (int i = 0; i < 16; ++i) { const int c = crow(i, h);
;             X[0][i] = (c >= r && c >= kneg) ? X[0][i] : -INFINITY; X[4][i] = (c <= r) ? X[4][i] : -INFINITY; }
	v_ashrrev_i32_e32 v7, 31, v6
	v_lshl_add_u64 v[6:7], s[4:5], 0, v[6:7]
	v_mad_u64_u32 v[4:5], s[2:3], v6, s10, v[4:5]
	v_mov_b32_e32 v6, v5
	v_mad_u64_u32 v[6:7], s[2:3], v7, s10, v[6:7]
	v_add_co_u32_e32 v12, vcc, s9, v4
	v_mov_b32_e32 v5, v6
	s_nop 0
	v_addc_co_u32_e32 v13, vcc, 0, v6, vcc
	global_load_dwordx4 v[126:129], v[10:11], off
	global_load_dwordx4 v[122:125], v[12:13], off
	global_load_dwordx4 v[118:121], v[8:9], off offset:2048
	global_load_dwordx4 v[114:117], v[4:5], off offset:2048
	v_bfe_u32 v17, v3, 5, 1
	v_writelane_b32 v254, s58, 14
	v_lshlrev_b32_e32 v170, 2, v17
	v_cmp_gt_u32_e64 s[4:5], v170, v162
	v_writelane_b32 v254, s59, 15
	v_or_b32_e32 v185, 26, v170
	v_writelane_b32 v254, s4, 12
	s_ashr_i32 s0, s0, 1
	v_cmp_lt_u32_e64 s[8:9], v185, v162
	v_writelane_b32 v254, s5, 13
	v_lshl_add_u64 v[158:159], s[84:85], 0, v[0:1]
	v_add_u32_e32 v4, 0, v0
	v_mov_b32_e32 v0, s0
	v_writelane_b32 v254, s8, 18
	v_bfi_b32 v0, s11, v0, v3
	s_movk_i32 s1, 0x90
	v_writelane_b32 v254, s9, 19
	v_cmp_gt_u32_e64 s[8:9], v185, v162
	v_and_b32_e32 v16, 63, v3
	s_and_b32 s33, s0, 0xffffffe0
	v_mul_lo_u32 v0, v0, s1
	v_bfe_u32 v7, v3, 2, 2
	v_writelane_b32 v254, s8, 16
	v_or_b32_e32 v186, 27, v170
	v_add_u32_e32 v5, 0, v0
	v_lshlrev_b32_e32 v0, 2, v16
	v_and_b32_e32 v3, 16, v3
	v_or3_b32 v7, v7, v170, s33
	s_movk_i32 s0, 0xc0
	v_writelane_b32 v254, s9, 17
	v_cmp_lt_u32_e64 s[8:9], v186, v162
	v_and_or_b32 v3, v0, 12, v3
	v_mul_lo_u32 v7, v7, s0
	v_writelane_b32 v254, s8, 20
	v_lshlrev_b32_e32 v3, 1, v3
	v_add_u32_e32 v7, 0, v7
	v_writelane_b32 v254, s9, 21
	v_cmp_gt_u32_e64 s[8:9], v186, v162
	v_lshlrev_b32_e32 v6, 4, v17
	v_xor_b32_e32 v171, 0x80, v0
	v_lshlrev_b32_e32 v0, 3, v17
	v_cmp_gt_u32_e64 s[88:89], 32, v16
	v_mul_lo_u32 v8, v163, s1
	v_mul_lo_u32 v9, v163, s0
	v_mul_lo_u32 v10, v164, s1
	v_mul_lo_u32 v11, v164, s0
	v_mul_lo_u32 v12, v165, s1
	v_mul_lo_u32 v13, v165, s0
	v_mul_lo_u32 v14, v166, s1
	v_mul_lo_u32 v15, v166, s0
	v_mul_lo_u32 v16, v167, s1
	v_mul_lo_u32 v17, v167, s0
	v_mul_lo_u32 v18, v168, s1
	v_mul_lo_u32 v19, v168, s0
	v_or_b32_e32 v172, 1, v170
	v_or_b32_e32 v173, 2, v170
	v_or_b32_e32 v174, 3, v170
	v_or_b32_e32 v175, 8, v170
	v_or_b32_e32 v176, 9, v170
	v_or_b32_e32 v177, 10, v170
	v_or_b32_e32 v178, 11, v170
	v_or_b32_e32 v179, 16, v170
	v_or_b32_e32 v180, 17, v170
	v_or_b32_e32 v181, 18, v170
	v_or_b32_e32 v182, 19, v170
	v_or_b32_e32 v183, 24, v170
	v_or_b32_e32 v184, 25, v170
	v_writelane_b32 v254, s8, 22
	v_add_u32_e32 v20, 0xd800, v7
	v_add_u32_e32 v200, v7, v3
	s_mov_b32 s93, 0
	v_cmp_lt_u32_e64 s[2:3], v170, v162
	v_cmp_lt_u32_e64 s[76:77], v172, v162
	v_cmp_lt_u32_e64 s[16:17], v173, v162
	v_cmp_gt_u32_e64 s[18:19], v173, v162
	v_cmp_lt_u32_e64 s[20:21], v174, v162
	v_cmp_gt_u32_e64 s[22:23], v174, v162
	v_cmp_lt_u32_e64 s[24:25], v175, v162
	v_cmp_gt_u32_e64 s[26:27], v175, v162
	v_cmp_lt_u32_e64 s[28:29], v176, v162
	v_cmp_gt_u32_e64 s[30:31], v176, v162
	v_cmp_lt_u32_e64 s[34:35], v177, v162
	v_cmp_gt_u32_e64 s[36:37], v177, v162
	v_cmp_lt_u32_e64 s[38:39], v178, v162
	v_cmp_gt_u32_e64 s[40:41], v178, v162
	v_cmp_lt_u32_e64 s[42:43], v179, v162
	v_cmp_gt_u32_e64 s[44:45], v179, v162
	v_cmp_lt_u32_e64 s[46:47], v180, v162
	v_cmp_gt_u32_e64 s[48:49], v180, v162
	v_cmp_lt_u32_e64 s[4:5], v181, v162
	v_cmp_gt_u32_e64 s[52:53], v181, v162
	v_cmp_lt_u32_e64 s[54:55], v182, v162
	v_cmp_gt_u32_e64 s[56:57], v182, v162
	v_cmp_lt_u32_e64 s[58:59], v183, v162
	v_cmp_gt_u32_e64 s[60:61], v183, v162
	v_cmp_lt_u32_e64 s[62:63], v184, v162
	v_cmp_gt_u32_e64 s[64:65], v184, v162
	v_writelane_b32 v254, s9, 23
	v_or_b32_e32 v246, 0x63, v170
	v_or_b32_e32 v190, 0x6a, v170
	v_or_b32_e32 v191, 0x6b, v170
	v_or_b32_e32 v192, 0x70, v170
	v_or_b32_e32 v193, 0x71, v170
	v_or_b32_e32 v194, 0x72, v170
	v_or_b32_e32 v195, 0x73, v170
	v_or_b32_e32 v196, 0x78, v170
	v_or_b32_e32 v197, 0x79, v170
	v_or_b32_e32 v198, 0x7a, v170
	v_or_b32_e32 v199, 0x7b, v170
	v_add_u32_e32 v201, 0xfc00, v200
	v_add_u32_e32 v202, 0xfc40, v200
	v_add_u32_e32 v203, v4, v8
	v_add_u32_e32 v208, v4, v9
	v_add_u32_e32 v209, v4, v10
	v_add_u32_e32 v210, v4, v11
	v_add_u32_e32 v211, v4, v12
	v_add_u32_e32 v212, v4, v13
	v_add_u32_e32 v213, v4, v14
	v_add_u32_e32 v214, v4, v15
	v_add_u32_e32 v215, v4, v16
	v_add_u32_e32 v216, v4, v17
	v_add_u32_e32 v217, v4, v18
	v_add_u32_e32 v218, v4, v19
	v_lshlrev_b32_e32 v160, 1, v2
	v_add_u32_e32 v219, v5, v6
	v_add_u32_e32 v220, v20, v3
	v_lshlrev_b32_e32 v0, 1, v0
	v_readlane_b32 s10, v255, 41
	s_add_i32 s10, s10, 64
	s_branch .Ldb_472

; #define LAS __attribute__((address_space(3)))
; __device__ __forceinline__ void phase(LAS unsigned char* L, const u16* __restrict__ QKV, u16* OBg0, u16* OBg1, u16* OBg2, float* LSE, int first, int stride, const int tid) {
;     ...
;     for (int kr = 0; kr < nround; ++kr) {
;         const int task = DL_TASK(kr);
;         const Dec d = decode(task);
; #pragma unroll
;         for (int n = 0; n < 6; ++n) { const int id = tid + 512 * n, c = id >> 3, ch = id & 7; *(LAS v4u*)(L + O_K + c * KP + ch * 16) = pk[n]; *(LAS v4u*)(L + O_V + c * VP + ch * 16) = pv[n]; }
;         bf16x8 qf[4];
; #pragma unroll
;         for (int ks = 0; ks < 4; ++ks) qf[ks] = qn[ks];
;         __syncthreads();
;         if (kr + 1 < nround) issue(QKV, DL_TASK(kr + 1), tid, pk, pv, qn);
;     ...
;         __syncthreads();
.Ldb_latch:
	s_add_i32 s10, s10, 0x60
	s_waitcnt vmcnt(4)
	v_mov_b64_e32 v[148:149], v[144:145]
	v_mov_b64_e32 v[152:153], v[140:141]
	v_mov_b64_e32 v[156:157], v[136:137]
	v_mov_b64_e32 v[66:67], v[130:131]
	s_cmp_lg_u32 s6, s93
	v_mov_b64_e32 v[146:147], v[142:143]
	v_mov_b64_e32 v[150:151], v[138:139]
	v_mov_b64_e32 v[154:155], v[134:135]
	v_mov_b64_e32 v[68:69], v[132:133]
	s_mov_b64 s[50:51], s[74:75]
	s_barrier
	s_cbranch_scc0 .Ldb_484

; __device__ __forceinline__ void phase(LAS unsigned char* L, const u16* __restrict__ QKV, u16* OBg0, u16* OBg1, u16* OBg2, float* LSE, int first, int stride, const int tid) {
;     ...
;         if (kr + 1 < nround) issue(QKV, DL_TASK(kr + 1), tid, pk, pv, qn);
.Ldb_477:
	v_readlane_b32 s12, v254, 12
	s_andn2_b64 vcc, exec, s[0:1]
	v_readlane_b32 s13, v254, 13
	s_cbranch_vccnz .Ldb_479
	s_add_i32 s11, s10, 0x60

; __device__ __forceinline__ float shx(float v, int m, int lane) { return __builtin_bit_cast(float, __builtin_amdgcn_ds_bpermute((lane ^ m) << 2, __builtin_bit_cast(int, v))); }
; __device__ __forceinline__ int crow(int r,int hi){return (r&3)+8*(r>>2)+4*hi;}
; __device__ __forceinline__ float shx(float v, int m, int lane) { return __builtin_bit_cast(float, __builtin_amdgcn_ds_bpermute((lane ^ m) << 2, __builtin_bit_cast(int, v))); }
; __device__ __forceinline__ int crow(int reg, int h) { return (reg & 3) + 8 * (reg >> 2) + 4 * h; }
; __device__ __forceinline__ void phase(LAS unsigned char* L, const u16* __restrict__ QKV, u16* OBg0, u16* OBg1, u16* OBg2, float* LSE, int first, int stride, const int tid) {
;     ...
;         float m = -INFINITY;
;         const int kneg = 128 - i0 - 32 * w;
; #pragma unroll
;         for (int i = 0; i < 16; ++i) { const int c = crow(i, h);
;             X[0][i] = (c >= r && c >= kneg) ? X[0][i] : -INFINITY; X[4][i] = (c <= r) ? X[4][i] : -INFINITY; }
;         if (kneg > 32) {
; #pragma unroll
;             for (int kb = 1; kb < 4; ++kb)
; #pragma unroll
;                 for (int i = 0; i < 16; ++i) X[kb][i] = (32 * kb + crow(i, h) >= kneg) ? X[kb][i] : -INFINITY;
;         }
; #pragma unroll
;         for (int kb = 0; kb < 5; ++kb)
; #pragma unroll
;             for (int i = 0; i < 16; i += 2) m = fmaxf(m, fmaxf(X[kb][i], X[kb][i + 1]));
;         m = fmaxf(m, shx(m, 32, lane));
;         float l = 0.f;
; #pragma unroll
;         for (int kb = 0; kb < 5; ++kb)
; #pragma unroll
;             for (int i = 0; i < 16; ++i) { X[kb][i] = __builtin_amdgcn_exp2f(X[kb][i] - m); l += X[kb][i]; }
;         l += shx(l, 32, lane);
.Ldb_482:
	v_cmp_gt_i32_e32 vcc, s13, v170
	s_or_b64 vcc, s[2:3], vcc
	s_nop 8
	v_cndmask_b32_e64 v146, v248, v67, s[2:3]
	v_cndmask_b32_e32 v150, v50, v248, vcc
	v_cmp_gt_i32_e32 vcc, s13, v172
	s_or_b64 vcc, s[76:77], vcc
	v_cndmask_b32_e64 v67, v71, v248, s[30:31]
	v_cndmask_b32_e32 v151, v51, v248, vcc
	v_cmp_gt_i32_e32 vcc, s13, v173
	s_or_b64 vcc, s[16:17], vcc
	v_cndmask_b32_e64 v147, v68, v248, s[18:19]
	v_cndmask_b32_e32 v152, v52, v248, vcc
	v_cmp_gt_i32_e32 vcc, s13, v174
	s_or_b64 vcc, s[20:21], vcc
	v_cndmask_b32_e64 v68, v72, v248, s[36:37]
	v_cndmask_b32_e32 v153, v53, v248, vcc
	v_cmp_gt_i32_e32 vcc, s13, v175
	s_or_b64 vcc, s[24:25], vcc
	v_cndmask_b32_e64 v148, v69, v248, s[22:23]
	v_cndmask_b32_e32 v154, v54, v248, vcc
	v_cmp_gt_i32_e32 vcc, s13, v176
	s_or_b64 vcc, s[28:29], vcc
	v_cndmask_b32_e64 v69, v73, v248, s[40:41]
	v_cndmask_b32_e32 v155, v55, v248, vcc
	v_cmp_gt_i32_e32 vcc, s13, v177
	s_or_b64 vcc, s[34:35], vcc
	v_readlane_b32 s50, v254, 12
	v_cndmask_b32_e32 v71, v56, v248, vcc
	v_cmp_gt_i32_e32 vcc, s13, v178
	s_or_b64 vcc, s[38:39], vcc
	v_readlane_b32 s51, v254, 13
	v_cndmask_b32_e32 v72, v57, v248, vcc
	v_cmp_gt_i32_e32 vcc, s13, v179
	s_or_b64 vcc, s[42:43], vcc
	v_cndmask_b32_e64 v149, v66, v248, s[50:51]
	v_cndmask_b32_e32 v73, v58, v248, vcc
	v_cmp_gt_i32_e32 vcc, s13, v180
	s_or_b64 vcc, s[46:47], vcc
	v_readlane_b32 s50, v254, 18
	v_cndmask_b32_e32 v59, v59, v248, vcc
	v_cmp_gt_i32_e32 vcc, s13, v181
	s_or_b64 vcc, s[4:5], vcc
	v_readlane_b32 s51, v254, 19
	v_cndmask_b32_e32 v60, v60, v248, vcc
	v_cmp_gt_i32_e32 vcc, s13, v182
	s_or_b64 vcc, s[54:55], vcc
	v_cndmask_b32_e32 v61, v61, v248, vcc
	v_cmp_gt_i32_e32 vcc, s13, v183
	s_or_b64 vcc, s[58:59], vcc
	v_cndmask_b32_e32 v62, v62, v248, vcc
	v_cmp_gt_i32_e32 vcc, s13, v184
	s_or_b64 vcc, s[62:63], vcc
	v_cndmask_b32_e64 v66, v74, v248, s[44:45]
	v_cndmask_b32_e32 v63, v63, v248, vcc
	v_cmp_gt_i32_e32 vcc, s13, v185
	s_or_b64 vcc, s[50:51], vcc
	v_cndmask_b32_e32 v64, v64, v248, vcc
	v_cmp_gt_i32_e32 vcc, s13, v186
	s_mov_b32 s13, 0xff800000
	v_cndmask_b32_e64 v56, v75, v248, s[48:49]
	v_readlane_b32 s50, v254, 16
	s_nop 1
	v_readlane_b32 s51, v254, 17
	s_nop 1
	v_cndmask_b32_e64 v53, v80, v248, s[50:51]
	v_readlane_b32 s50, v254, 20
	s_nop 1
	v_readlane_b32 s51, v254, 21
	s_nop 1
	s_or_b64 vcc, s[50:51], vcc
	v_cndmask_b32_e32 v65, v65, v248, vcc
	v_cndmask_b32_e64 v70, v70, v248, s[26:27]
	v_cndmask_b32_e64 v57, v76, v248, s[52:53]
	v_cndmask_b32_e64 v58, v77, v248, s[56:57]
	v_readlane_b32 s50, v254, 22
	v_cndmask_b32_e64 v55, v78, v248, s[60:61]
	v_cndmask_b32_e64 v51, v79, v248, s[64:65]
	v_readlane_b32 s51, v254, 23
	s_nop 1
	v_cndmask_b32_e64 v54, v81, v248, s[50:51]
	v_max3_f32 v52, v151, v150, v153
	v_max3_f32 v74, v152, v155, v154
	v_max3_f32 v52, v52, v72, v71
	v_max3_f32 v74, v74, v59, v73
	v_max3_f32 v52, v52, v61, v60
	v_max3_f32 v74, v74, v63, v62
	v_max3_f32 v52, v52, v65, v64
	v_max3_f32 v74, v74, v35, v34
	v_max3_f32 v52, v52, v37, v36
	v_max3_f32 v74, v74, v39, v38
	v_max3_f32 v52, v52, v41, v40
	v_max3_f32 v74, v74, v43, v42
	v_max3_f32 v52, v52, v45, v44
	v_max3_f32 v74, v74, v47, v46
	v_max3_f32 v52, v52, v49, v48
	v_max3_f32 v74, v74, v19, v18
	v_max3_f32 v52, v52, v21, v20
	v_max3_f32 v74, v74, v23, v22
	v_max3_f32 v52, v52, v25, v24
	v_max3_f32 v74, v74, v27, v26
	v_max3_f32 v52, v52, v29, v28
	v_max3_f32 v74, v74, v31, v30
	v_max3_f32 v52, v52, v33, v32
	v_max3_f32 v74, v74, v3, v2
	v_max3_f32 v52, v52, v5, v4
	v_max3_f32 v74, v74, v7, v6
	v_max3_f32 v52, v52, v9, v8
	v_max3_f32 v74, v74, v11, v10
	v_max3_f32 v52, v52, v13, v12
	v_max3_f32 v74, v74, v15, v14
	v_max3_f32 v52, v52, v17, v16
	v_max3_f32 v74, v74, v146, v149
	v_max3_f32 v52, v52, v148, v147
	v_max3_f32 v74, v74, v67, v70
	v_max3_f32 v52, v52, v69, v68
	v_max3_f32 v74, v74, v56, v66
	v_max3_f32 v52, v52, v58, v57
	v_max3_f32 v74, v74, v51, v55
	v_max3_f32 v52, v52, v54, v53
	v_max_f32_e32 v52, v52, v74
	ds_bpermute_b32 v74, v171, v52
	s_ashr_i32 vcc_lo, s68, 4
	s_sub_i32 s14, 5, s9
	v_or_b32_e32 v50, s12, v162
	s_ashr_i32 vcc_hi, vcc_lo, 31
	s_waitcnt lgkmcnt(0)
	v_max_f32_e32 v74, v74, v74
	v_max_f32_e32 v52, v52, v74
	v_sub_f32_e32 v74, v150, v52
	v_exp_f32_e32 v74, v74
	v_sub_f32_e32 v75, v151, v52
	v_exp_f32_e32 v75, v75
	v_sub_f32_e32 v76, v152, v52
	v_exp_f32_e32 v76, v76
	v_sub_f32_e32 v78, v153, v52
	v_exp_f32_e32 v78, v78
	v_sub_f32_e32 v79, v154, v52
	v_add_f32_e32 v77, 0, v74
	v_exp_f32_e32 v79, v79
	v_sub_f32_e32 v80, v155, v52
	v_add_f32_e32 v77, v75, v77
	v_exp_f32_e32 v80, v80
	v_sub_f32_e32 v71, v71, v52
	v_add_f32_e32 v77, v76, v77
	v_exp_f32_e32 v71, v71
	v_sub_f32_e32 v72, v72, v52
	v_add_f32_e32 v77, v78, v77
	v_exp_f32_e32 v72, v72
	v_sub_f32_e32 v73, v73, v52
	v_add_f32_e32 v77, v79, v77
	v_exp_f32_e32 v73, v73
	v_sub_f32_e32 v59, v59, v52
	v_add_f32_e32 v77, v80, v77
	v_exp_f32_e32 v59, v59
	v_sub_f32_e32 v60, v60, v52
	v_add_f32_e32 v77, v71, v77
	v_exp_f32_e32 v60, v60
	v_sub_f32_e32 v61, v61, v52
	v_add_f32_e32 v77, v72, v77
	v_exp_f32_e32 v61, v61
	v_sub_f32_e32 v62, v62, v52
	v_add_f32_e32 v77, v73, v77
	v_exp_f32_e32 v62, v62
	v_sub_f32_e32 v63, v63, v52
	v_add_f32_e32 v77, v59, v77
	v_exp_f32_e32 v63, v63
	v_sub_f32_e32 v64, v64, v52
	v_add_f32_e32 v77, v60, v77
	v_exp_f32_e32 v64, v64
	v_sub_f32_e32 v65, v65, v52
	v_add_f32_e32 v77, v61, v77
	v_exp_f32_e32 v65, v65
	v_sub_f32_e32 v34, v34, v52
	v_add_f32_e32 v77, v62, v77
	v_exp_f32_e32 v81, v34
	v_sub_f32_e32 v34, v35, v52
	v_add_f32_e32 v77, v63, v77
	v_exp_f32_e32 v150, v34
	v_sub_f32_e32 v34, v36, v52
	v_add_f32_e32 v77, v64, v77
	v_exp_f32_e32 v151, v34
	v_sub_f32_e32 v35, v37, v52
; __device__ __forceinline__ float shx(float v, int m, int lane) { return __builtin_bit_cast(float, __builtin_amdgcn_ds_bpermute((lane ^ m) << 2, __builtin_bit_cast(int, v))); }
; __device__ __forceinline__ float shx(float v, int m, int lane) { return __builtin_bit_cast(float, __builtin_amdgcn_ds_bpermute((lane ^ m) << 2, __builtin_bit_cast(int, v))); }
; #define MFMA32(a, b, c) __builtin_amdgcn_mfma_f32_32x32x16_bf16((a), (b), (c), 0, 0, 0)
; __device__ __forceinline__ void phase(LAS unsigned char* L, const u16* __restrict__ QKV, u16* OBg0, u16* OBg1, u16* OBg2, float* LSE, int first, int stride, const int tid) {
;     ...
;         float l = 0.f;
; #pragma unroll
;         for (int kb = 0; kb < 5; ++kb)
; #pragma unroll
;             for (int i = 0; i < 16; ++i) { X[kb][i] = __builtin_amdgcn_exp2f(X[kb][i] - m); l += X[kb][i]; }
;         l += shx(l, 32, lane);
;         f32x16 y[2]; y[0] = f32x16{}; y[1] = f32x16{};
; #pragma unroll
;         for (int kb = 0; kb < 5; ++kb) {
;             bf16x8 vf[2][2];
; #pragma unroll
;             for (int s2 = 0; s2 < 2; ++s2)
; #pragma unroll
;                 for (int dt = 0; dt < 2; ++dt) vf[s2][dt] = trfrag(L + O_V, VP, 32 * w + 32 * kb + 16 * s2 + 4 * h, 8, 32 * dt, lane);
;             const bf16x8 pb0 = pack8(X[kb], 0), pb1 = pack8(X[kb], 8);
;             y[0] = MFMA32(vf[0][0], pb0, y[0]); y[1] = MFMA32(vf[0][1], pb0, y[1]); y[0] = MFMA32(vf[1][0], pb1, y[0]); y[1] = MFMA32(vf[1][1], pb1, y[1]);
;         }
	v_add_f32_e32 v34, v65, v77
	v_exp_f32_e32 v77, v35
	v_sub_f32_e32 v35, v38, v52
	v_add_f32_e32 v34, v81, v34
	v_exp_f32_e32 v152, v35
	v_sub_f32_e32 v35, v39, v52
	v_add_f32_e32 v34, v150, v34
	v_exp_f32_e32 v153, v35
	v_sub_f32_e32 v35, v40, v52
	v_add_f32_e32 v34, v151, v34
	v_exp_f32_e32 v154, v35
	v_sub_f32_e32 v35, v41, v52
	v_add_f32_e32 v34, v77, v34
	v_exp_f32_e32 v155, v35
	v_sub_f32_e32 v35, v42, v52
	v_add_f32_e32 v34, v152, v34
	v_exp_f32_e32 v156, v35
	v_sub_f32_e32 v35, v43, v52
	v_add_f32_e32 v34, v153, v34
	v_exp_f32_e32 v157, v35
	v_sub_f32_e32 v35, v44, v52
	v_add_f32_e32 v34, v154, v34
	v_exp_f32_e32 v161, v35
	v_sub_f32_e32 v35, v45, v52
	v_add_f32_e32 v34, v155, v34
	v_exp_f32_e32 v204, v35
	v_sub_f32_e32 v35, v46, v52
	v_add_f32_e32 v34, v156, v34
	v_exp_f32_e32 v46, v35
	v_sub_f32_e32 v35, v47, v52
	v_add_f32_e32 v34, v157, v34
	v_exp_f32_e32 v47, v35
	v_sub_f32_e32 v35, v48, v52
	v_add_f32_e32 v34, v161, v34
	v_exp_f32_e32 v48, v35
	v_sub_f32_e32 v35, v49, v52
	v_add_f32_e32 v34, v204, v34
	v_exp_f32_e32 v49, v35
	v_sub_f32_e32 v18, v18, v52
	v_add_f32_e32 v34, v46, v34
	v_exp_f32_e32 v205, v18
	v_sub_f32_e32 v18, v19, v52
	v_add_f32_e32 v34, v47, v34
	v_exp_f32_e32 v206, v18
	v_sub_f32_e32 v18, v20, v52
	v_add_f32_e32 v34, v48, v34
	v_exp_f32_e32 v207, v18
	v_sub_f32_e32 v19, v21, v52
	v_add_f32_e32 v18, v49, v34
	v_exp_f32_e32 v221, v19
	v_sub_f32_e32 v19, v22, v52
	v_add_f32_e32 v18, v205, v18
	v_exp_f32_e32 v222, v19
	v_sub_f32_e32 v19, v23, v52
	v_add_f32_e32 v18, v206, v18
	v_exp_f32_e32 v223, v19
	v_sub_f32_e32 v19, v24, v52
	v_add_f32_e32 v18, v207, v18
	v_exp_f32_e32 v224, v19
	v_sub_f32_e32 v19, v25, v52
	v_add_f32_e32 v18, v221, v18
	v_exp_f32_e32 v225, v19
	v_sub_f32_e32 v19, v26, v52
	v_add_f32_e32 v18, v222, v18
	v_exp_f32_e32 v226, v19
	v_sub_f32_e32 v19, v27, v52
	v_add_f32_e32 v18, v223, v18
	v_exp_f32_e32 v227, v19
	v_sub_f32_e32 v19, v28, v52
	v_add_f32_e32 v18, v224, v18
	v_exp_f32_e32 v228, v19
	v_sub_f32_e32 v19, v29, v52
	v_add_f32_e32 v18, v225, v18
	v_exp_f32_e32 v229, v19
	v_sub_f32_e32 v19, v30, v52
	v_add_f32_e32 v18, v226, v18
	v_exp_f32_e32 v230, v19
	v_sub_f32_e32 v19, v31, v52
	v_add_f32_e32 v18, v227, v18
	v_exp_f32_e32 v231, v19
	v_sub_f32_e32 v19, v32, v52
	v_add_f32_e32 v18, v228, v18
	v_exp_f32_e32 v232, v19
	v_sub_f32_e32 v19, v33, v52
	v_add_f32_e32 v18, v229, v18
	v_exp_f32_e32 v233, v19
	v_sub_f32_e32 v2, v2, v52
	v_add_f32_e32 v18, v230, v18
	v_exp_f32_e32 v234, v2
	v_sub_f32_e32 v2, v3, v52
	v_add_f32_e32 v18, v231, v18
	v_exp_f32_e32 v235, v2
	v_sub_f32_e32 v2, v4, v52
	v_add_f32_e32 v18, v232, v18
	v_exp_f32_e32 v236, v2
	v_sub_f32_e32 v3, v5, v52
	v_add_f32_e32 v2, v233, v18
	v_exp_f32_e32 v237, v3
	v_sub_f32_e32 v3, v6, v52
	v_add_f32_e32 v2, v234, v2
	v_exp_f32_e32 v238, v3
	v_sub_f32_e32 v3, v7, v52
	v_add_f32_e32 v2, v235, v2
	v_exp_f32_e32 v239, v3
	v_sub_f32_e32 v3, v8, v52
	v_add_f32_e32 v2, v236, v2
	v_exp_f32_e32 v240, v3
	v_sub_f32_e32 v3, v9, v52
	v_add_f32_e32 v2, v237, v2
	v_exp_f32_e32 v241, v3
	v_sub_f32_e32 v3, v10, v52
	v_add_f32_e32 v2, v238, v2
	v_exp_f32_e32 v242, v3
	v_sub_f32_e32 v3, v11, v52
	v_add_f32_e32 v2, v239, v2
	v_exp_f32_e32 v243, v3
	v_sub_f32_e32 v3, v12, v52
	v_add_f32_e32 v2, v240, v2
	v_exp_f32_e32 v244, v3
	v_add_f32_e32 v2, v241, v2
	v_add_f32_e32 v2, v242, v2
	v_add_f32_e32 v2, v243, v2
	v_add_f32_e32 v6, v244, v2
	v_sub_f32_e32 v2, v13, v52
	v_exp_f32_e32 v245, v2
	v_sub_f32_e32 v2, v14, v52
	v_exp_f32_e32 v251, v2
	ds_read_b64_tr_b16 v[2:3], v200 offset:55296
	ds_read_b64_tr_b16 v[4:5], v200 offset:56832
	v_add_f32_e32 v6, v245, v6
	v_cvt_pk_bf16_f32 v10, v74, v75
	v_cvt_pk_bf16_f32 v11, v76, v78
	v_cvt_pk_bf16_f32 v12, v79, v80
	v_cvt_pk_bf16_f32 v13, v71, v72
	v_add_f32_e32 v252, v251, v6
	ds_read_b64_tr_b16 v[8:9], v200 offset:56896
	ds_read_b64_tr_b16 v[6:7], v200 offset:55360
	s_waitcnt lgkmcnt(2)
	v_mfma_f32_32x32x16_bf16 v[18:33], v[2:5], v[10:13], 0
	v_sub_f32_e32 v2, v15, v52
	ds_read_b64_tr_b16 v[34:35], v200 offset:58368
	ds_read_b64_tr_b16 v[36:37], v200 offset:59904
	v_exp_f32_e32 v71, v2
	v_sub_f32_e32 v2, v16, v52
	v_exp_f32_e32 v72, v2
	v_sub_f32_e32 v38, v17, v52
	v_exp_f32_e32 v74, v38
	s_waitcnt lgkmcnt(2)
	v_mfma_f32_32x32x16_bf16 v[2:17], v[6:9], v[10:13], 0
	v_cvt_pk_bf16_f32 v42, v73, v59
	v_cvt_pk_bf16_f32 v43, v60, v61
	v_cvt_pk_bf16_f32 v44, v62, v63
	v_cvt_pk_bf16_f32 v45, v64, v65
	ds_read_b64_tr_b16 v[40:41], v200 offset:59968
	ds_read_b64_tr_b16 v[38:39], v200 offset:58432
	v_sub_f32_e32 v63, v148, v52
	v_exp_f32_e32 v63, v63
	s_waitcnt lgkmcnt(2)
	v_mfma_f32_32x32x16_bf16 v[18:33], v[34:37], v[42:45], v[18:33]
	v_add_f32_e32 v34, v71, v252
	v_add_f32_e32 v34, v72, v34
	v_add_f32_e32 v59, v74, v34
	v_sub_f32_e32 v34, v149, v52
	v_exp_f32_e32 v60, v34
	ds_read_b64_tr_b16 v[34:35], v200 offset:61440
	ds_read_b64_tr_b16 v[36:37], v200 offset:62976
	v_sub_f32_e32 v58, v58, v52
	s_waitcnt lgkmcnt(2)
	v_mfma_f32_32x32x16_bf16 v[2:17], v[38:41], v[42:45], v[2:17]
	v_cvt_pk_bf16_f32 v42, v81, v150
	v_cvt_pk_bf16_f32 v43, v151, v77
	v_cvt_pk_bf16_f32 v44, v152, v153
	v_cvt_pk_bf16_f32 v45, v154, v155
	ds_read_b64_tr_b16 v[40:41], v200 offset:63040
	ds_read_b64_tr_b16 v[38:39], v200 offset:61504
	v_add_f32_e32 v59, v60, v59
	v_exp_f32_e32 v58, v58
	s_waitcnt lgkmcnt(2)
	v_mfma_f32_32x32x16_bf16 v[18:33], v[34:37], v[42:45], v[18:33]
	v_sub_f32_e32 v34, v146, v52
	v_exp_f32_e32 v61, v34
	v_sub_f32_e32 v34, v147, v52
	v_exp_f32_e32 v62, v34
	ds_read_b64_tr_b16 v[34:35], v200 offset:64512
	ds_read_b64_tr_b16 v[36:37], v201 offset:1536
	s_lshr_b32 s11, s11, s14
	v_lshlrev_b32_e32 v50, s9, v50
	s_waitcnt lgkmcnt(2)
; #define MFMA32(a, b, c) __builtin_amdgcn_mfma_f32_32x32x16_bf16((a), (b), (c), 0, 0, 0)
; __device__ __forceinline__ void phase(LAS unsigned char* L, const u16* __restrict__ QKV, u16* OBg0, u16* OBg1, u16* OBg2, float* LSE, int first, int stride, const int tid) {
;     ...
;         f32x16 y[2]; y[0] = f32x16{}; y[1] = f32x16{};
; #pragma unroll
;         for (int kb = 0; kb < 5; ++kb) {
;             bf16x8 vf[2][2];
; #pragma unroll
;             for (int s2 = 0; s2 < 2; ++s2)
; #pragma unroll
;                 for (int dt = 0; dt < 2; ++dt) vf[s2][dt] = trfrag(L + O_V, VP, 32 * w + 32 * kb + 16 * s2 + 4 * h, 8, 32 * dt, lane);
;             const bf16x8 pb0 = pack8(X[kb], 0), pb1 = pack8(X[kb], 8);
;             y[0] = MFMA32(vf[0][0], pb0, y[0]); y[1] = MFMA32(vf[0][1], pb0, y[1]); y[0] = MFMA32(vf[1][0], pb1, y[0]); y[1] = MFMA32(vf[1][1], pb1, y[1]);
;         }
;         const float inv = __builtin_amdgcn_rcpf(l);
	v_mfma_f32_32x32x16_bf16 v[2:17], v[38:41], v[42:45], v[2:17]
	v_cvt_pk_bf16_f32 v42, v156, v157
	v_cvt_pk_bf16_f32 v43, v161, v204
	v_cvt_pk_bf16_f32 v44, v46, v47
	v_cvt_pk_bf16_f32 v45, v48, v49
	ds_read_b64_tr_b16 v[40:41], v202 offset:1536
	ds_read_b64_tr_b16 v[38:39], v200 offset:64576
	s_and_b32 s9, s68, 15
	s_lshl_b64 s[12:13], vcc, 13
	s_waitcnt lgkmcnt(2)
	v_mfma_f32_32x32x16_bf16 v[18:33], v[34:37], v[42:45], v[18:33]
	v_add_f32_e32 v34, v61, v59
	v_add_f32_e32 v34, v62, v34
	v_add_f32_e32 v46, v63, v34
	v_sub_f32_e32 v34, v70, v52
	v_exp_f32_e32 v47, v34
	ds_read_b64_tr_b16 v[34:35], v220 offset:12288
	ds_read_b64_tr_b16 v[36:37], v220 offset:13824
	v_sub_f32_e32 v59, v69, v52
	s_waitcnt lgkmcnt(2)
	v_mfma_f32_32x32x16_bf16 v[2:17], v[38:41], v[42:45], v[2:17]
	v_cvt_pk_bf16_f32 v42, v205, v206
	v_cvt_pk_bf16_f32 v43, v207, v221
	v_cvt_pk_bf16_f32 v44, v222, v223
	v_cvt_pk_bf16_f32 v45, v224, v225
	ds_read_b64_tr_b16 v[40:41], v220 offset:13888
	ds_read_b64_tr_b16 v[38:39], v220 offset:12352
	v_exp_f32_e32 v59, v59
	v_add_f32_e32 v46, v47, v46
	s_waitcnt lgkmcnt(2)
	v_mfma_f32_32x32x16_bf16 v[18:33], v[34:37], v[42:45], v[18:33]
	v_sub_f32_e32 v34, v67, v52
	v_exp_f32_e32 v48, v34
	v_sub_f32_e32 v34, v68, v52
	v_exp_f32_e32 v49, v34
	ds_read_b64_tr_b16 v[34:35], v220 offset:15360
	ds_read_b64_tr_b16 v[36:37], v220 offset:16896
	v_add_u32_e32 v50, s11, v50
	s_cmp_eq_u32 s0, 1
	s_waitcnt lgkmcnt(2)
	v_mfma_f32_32x32x16_bf16 v[2:17], v[38:41], v[42:45], v[2:17]
	v_cvt_pk_bf16_f32 v42, v226, v227
	v_cvt_pk_bf16_f32 v43, v228, v229
	v_cvt_pk_bf16_f32 v44, v230, v231
	v_cvt_pk_bf16_f32 v45, v232, v233
	ds_read_b64_tr_b16 v[40:41], v220 offset:16960
	ds_read_b64_tr_b16 v[38:39], v220 offset:15424
	v_readlane_b32 s11, v255, 1
	v_readlane_b32 s14, v255, 2
	s_waitcnt lgkmcnt(2)
	v_mfma_f32_32x32x16_bf16 v[18:33], v[34:37], v[42:45], v[18:33]
	v_add_f32_e32 v34, v48, v46
	v_add_f32_e32 v34, v49, v34
	v_add_f32_e32 v46, v59, v34
	v_sub_f32_e32 v34, v66, v52
	v_exp_f32_e32 v64, v34
	ds_read_b64_tr_b16 v[34:35], v220 offset:18432
	ds_read_b64_tr_b16 v[36:37], v220 offset:19968
	s_cselect_b32 s11, s11, s80
	s_waitcnt lgkmcnt(2)
	v_mfma_f32_32x32x16_bf16 v[2:17], v[38:41], v[42:45], v[2:17]
	v_cvt_pk_bf16_f32 v42, v234, v235
	v_cvt_pk_bf16_f32 v43, v236, v237
	v_cvt_pk_bf16_f32 v44, v238, v239
	v_cvt_pk_bf16_f32 v45, v240, v241
	ds_read_b64_tr_b16 v[40:41], v220 offset:20032
	ds_read_b64_tr_b16 v[38:39], v220 offset:18496
	v_add_f32_e32 v46, v64, v46
	s_cselect_b32 s14, s14, s81
	s_waitcnt lgkmcnt(2)
	v_mfma_f32_32x32x16_bf16 v[18:33], v[34:37], v[42:45], v[18:33]
	v_sub_f32_e32 v34, v56, v52
	v_exp_f32_e32 v56, v34
	v_sub_f32_e32 v34, v57, v52
	v_exp_f32_e32 v57, v34
	ds_read_b64_tr_b16 v[34:35], v220 offset:21504
	ds_read_b64_tr_b16 v[36:37], v220 offset:23040
	s_cmp_lt_u32 s1, 32
	v_readlane_b32 s1, v253, 58
	s_waitcnt lgkmcnt(2)
	v_mfma_f32_32x32x16_bf16 v[2:17], v[38:41], v[42:45], v[2:17]
	v_cvt_pk_bf16_f32 v42, v242, v243
	v_cvt_pk_bf16_f32 v43, v244, v245
	v_cvt_pk_bf16_f32 v44, v251, v71
	v_cvt_pk_bf16_f32 v45, v72, v74
	ds_read_b64_tr_b16 v[40:41], v220 offset:23104
	ds_read_b64_tr_b16 v[38:39], v220 offset:21568
	s_cselect_b32 s15, s1, s14
	v_readlane_b32 s1, v253, 57
	s_waitcnt lgkmcnt(2)
	v_mfma_f32_32x32x16_bf16 v[18:33], v[34:37], v[42:45], v[18:33]
	v_add_f32_e32 v34, v56, v46
	v_add_f32_e32 v34, v57, v34
	v_add_f32_e32 v46, v58, v34
	v_sub_f32_e32 v34, v55, v52
	v_exp_f32_e32 v55, v34
	ds_read_b64_tr_b16 v[34:35], v220 offset:24576
	ds_read_b64_tr_b16 v[36:37], v220 offset:26112
	s_cselect_b32 s14, s1, s11
	s_waitcnt lgkmcnt(2)
	v_mfma_f32_32x32x16_bf16 v[2:17], v[38:41], v[42:45], v[2:17]
	v_cvt_pk_bf16_f32 v42, v60, v61
	v_cvt_pk_bf16_f32 v43, v62, v63
	v_cvt_pk_bf16_f32 v44, v47, v48
	v_cvt_pk_bf16_f32 v45, v49, v59
	ds_read_b64_tr_b16 v[40:41], v220 offset:26176
	ds_read_b64_tr_b16 v[38:39], v220 offset:24640
	v_sub_f32_e32 v49, v54, v52
	v_exp_f32_e32 v49, v49
	s_waitcnt lgkmcnt(2)
	v_mfma_f32_32x32x16_bf16 v[18:33], v[34:37], v[42:45], v[18:33]
	v_sub_f32_e32 v34, v51, v52
	v_exp_f32_e32 v47, v34
	v_sub_f32_e32 v34, v53, v52
	v_exp_f32_e32 v48, v34
	ds_read_b64_tr_b16 v[34:35], v220 offset:27648
	ds_read_b64_tr_b16 v[36:37], v220 offset:29184
	v_add_f32_e32 v46, v55, v46
	v_ashrrev_i32_e32 v51, 31, v50
	s_waitcnt lgkmcnt(2)
	v_mfma_f32_32x32x16_bf16 v[2:17], v[38:41], v[42:45], v[2:17]
	v_cvt_pk_bf16_f32 v42, v64, v56
	v_cvt_pk_bf16_f32 v43, v57, v58
	v_cvt_pk_bf16_f32 v44, v55, v47
	v_cvt_pk_bf16_f32 v45, v48, v49
	ds_read_b64_tr_b16 v[40:41], v220 offset:29248
	ds_read_b64_tr_b16 v[38:39], v220 offset:27712
	s_lshl_b32 s68, s9, 7
	s_waitcnt lgkmcnt(2)
	v_mfma_f32_32x32x16_bf16 v[18:33], v[34:37], v[42:45], v[18:33]
	v_add_f32_e32 v34, v47, v46
	v_add_f32_e32 v34, v48, v34
	v_add_f32_e32 v34, v49, v34
	ds_bpermute_b32 v35, v171, v34
	s_waitcnt lgkmcnt(0)
; __device__ __forceinline__ void phase(LAS unsigned char* L, const u16* __restrict__ QKV, u16* OBg0, u16* OBg1, u16* OBg2, float* LSE, int first, int stride, const int tid) {
;     ...
;         const float inv = __builtin_amdgcn_rcpf(l);
;         u16* ob = (g == 0 ? OBg0 : g == 1 ? OBg1 : OBg2) + (d.rowb + qpos) * 1024 + d.hd * 64;
; #pragma unroll
;         for (int dt = 0; dt < 2; ++dt)
; #pragma unroll
;             for (int gp = 0; gp < 2; ++gp) {
;                 const int ge = 2 * gp, go = 2 * gp + 1;
;                 unsigned e0 = pk2(y[dt][4 * ge] * inv, y[dt][4 * ge + 1] * inv), e1 = pk2(y[dt][4 * ge + 2] * inv, y[dt][4 * ge + 3] * inv);
;                 unsigned o0 = pk2(y[dt][4 * go] * inv, y[dt][4 * go + 1] * inv), o1 = pk2(y[dt][4 * go + 2] * inv, y[dt][4 * go + 3] * inv);
;                 const auto s0 = __builtin_amdgcn_permlane32_swap(e0, o0, false, false); const auto s1 = __builtin_amdgcn_permlane32_swap(e1, o1, false, false);
;                 const v4u wv = {s0[0], s1[0], s0[1], s1[1]};
;                 *(v4u*)(ob + 32 * dt + 8 * (2 * gp + h)) = wv; }
;         if (h == 0) LSE[((size_t)g * MTOK + d.rowb + qpos) * 16 + d.hd] = (m + __log2f(l)) * 0.6931471805599453f;
; __device__ __forceinline__ void dil_merge(const u16* OB0, const u16* OB1, const u16* OB2, const float* LSE, u16* MIX, int gw, int NGW, int lane) {
;     ...
;         const float l0 = LSE[((size_t)m) * 16 + hd], l1 = LSE[((size_t)MTOK + m) * 16 + hd], l2 = LSE[((size_t)2 * MTOK + m) * 16 + hd];
;         const float mx = fmaxf(l0, fmaxf(l1, l2)); float w0 = __expf(l0 - mx), w1 = __expf(l1 - mx), w2 = __expf(l2 - mx); const float iz = 1.f / (w0 + w1 + w2); w0 *= iz; w1 *= iz; w2 *= iz;
;         const size_t off = (size_t)m * 1024 + hd * 64 + dq;
; #pragma unroll
;         for (int j = 0; j < 2; ++j) { const v4u a = *(const v4u*)(OB0 + off + 8 * j), bq = *(const v4u*)(OB1 + off + 8 * j), c = *(const v4u*)(OB2 + off + 8 * j);
;             const unsigned aw[4] = {a.x, a.y, a.z, a.w}, bw[4] = {bq.x, bq.y, bq.z, bq.w}, cw[4] = {c.x, c.y, c.z, c.w}; unsigned ow[4];
; #pragma unroll
;             for (int e = 0; e < 4; ++e) ow[e] = pk2(w0 * bflo(aw[e]) + w1 * bflo(bw[e]) + w2 * bflo(cw[e]), w0 * bfhi(aw[e]) + w1 * bfhi(bw[e]) + w2 * bfhi(cw[e]));
;             *(v4u*)(MIX + off + 8 * j) = (v4u){ow[0], ow[1], ow[2], ow[3]}; }
	v_add_f32_e32 v36, v34, v35
	v_mfma_f32_32x32x16_bf16 v[2:17], v[38:41], v[42:45], v[2:17]
	v_rcp_f32_e32 v38, v36
	v_lshl_add_u64 v[34:35], s[12:13], 0, v[50:51]
	v_lshlrev_b64 v[40:41], 11, v[34:35]
	v_lshl_add_u64 v[40:41], s[14:15], 0, v[40:41]
	v_lshl_add_u64 v[66:67], v[40:41], 0, s[68:69]
	s_mov_b64 s[98:99], 0x14000000
	v_lshlrev_b64 v[80:81], 6, v[34:35]
	v_lshl_add_u64 v[66:67], v[66:67], 0, v[0:1]
	v_readlane_b32 s0, v253, 63
	v_readlane_b32 s1, v255, 0
	v_lshl_add_u64 v[68:69], v[66:67], 0, s[98:99]
	s_lshl_b32 s98, s9, 2
	s_mov_b32 s99, 0
	v_lshl_add_u64 v[80:81], s[0:1], 0, v[80:81]
	s_mov_b64 s[0:1], 0x200000
	v_lshl_add_u64 v[80:81], v[80:81], 0, s[98:99]
	s_mov_b64 s[98:99], 0x18000000
	global_load_dword v242, v[80:81], off
	v_lshl_add_u64 v[80:81], v[80:81], 0, s[0:1]
	global_load_dword v243, v[80:81], off
	global_load_dwordx4 v[146:149], v[68:69], off nt
	global_load_dwordx4 v[150:153], v[68:69], off offset:64 nt
	global_load_dwordx4 v[154:157], v[68:69], off offset:32 nt
	global_load_dwordx4 v[204:207], v[68:69], off offset:96 nt
	v_lshl_add_u64 v[68:69], v[66:67], 0, s[98:99]
	s_nop 0
	global_load_dwordx4 v[226:229], v[68:69], off nt
	global_load_dwordx4 v[230:233], v[68:69], off offset:64 nt
	global_load_dwordx4 v[234:237], v[68:69], off offset:32 nt
	global_load_dwordx4 v[238:241], v[68:69], off offset:96 nt
	s_nop 0
	v_pk_mul_f32 v[18:19], v[18:19], v[38:39] op_sel_hi:[1,0]
	v_pk_mul_f32 v[20:21], v[20:21], v[38:39] op_sel_hi:[1,0]
	v_cvt_pk_bf16_f32 v18, v18, v19
	s_nop 3
	v_pk_mul_f32 v[2:3], v[2:3], v[38:39] op_sel_hi:[1,0]
	v_pk_mul_f32 v[4:5], v[4:5], v[38:39] op_sel_hi:[1,0]
	v_cvt_pk_bf16_f32 v19, v20, v21
	v_pk_mul_f32 v[20:21], v[22:23], v[38:39] op_sel_hi:[1,0]
	v_pk_mul_f32 v[22:23], v[24:25], v[38:39] op_sel_hi:[1,0]
	v_cvt_pk_bf16_f32 v2, v2, v3
	v_cvt_pk_bf16_f32 v3, v4, v5
	v_pk_mul_f32 v[4:5], v[6:7], v[38:39] op_sel_hi:[1,0]
	v_pk_mul_f32 v[6:7], v[8:9], v[38:39] op_sel_hi:[1,0]
	v_lshl_add_u64 v[40:41], v[40:41], 0, s[68:69]
	v_cvt_pk_bf16_f32 v20, v20, v21
	v_cvt_pk_bf16_f32 v21, v22, v23
	v_cvt_pk_bf16_f32 v4, v4, v5
	v_cvt_pk_bf16_f32 v5, v6, v7
	v_permlane32_swap_b32_e32 v18, v20
	v_permlane32_swap_b32_e32 v19, v21
	v_lshl_add_u64 v[22:23], v[40:41], 0, v[0:1]
	v_permlane32_swap_b32_e32 v2, v4
	v_permlane32_swap_b32_e32 v3, v5
	s_mov_b64 s[0:1], 0x4000000
	v_log_f32_e32 v221, v36
	s_nop 0
	v_lshl_add_u64 v[22:23], v[22:23], 0, s[0:1]
	v_add_f32_e32 v221, v52, v221
	v_mul_f32_e32 v221, 0x3f317218, v221
	s_waitcnt vmcnt(0)
	v_max3_f32 v222, v242, v243, v221
	v_sub_f32_e32 v223, v242, v222
	v_mul_f32_e32 v223, 0x3fb8aa3b, v223
	v_exp_f32_e32 v244, v223
	v_sub_f32_e32 v223, v243, v222
	v_mul_f32_e32 v223, 0x3fb8aa3b, v223
	v_exp_f32_e32 v245, v223
	v_sub_f32_e32 v223, v221, v222
	v_mul_f32_e32 v223, 0x3fb8aa3b, v223
	v_exp_f32_e32 v224, v223
	s_nop 0
	v_add_f32_e32 v221, v244, v245
	v_add_f32_e32 v221, v224, v221
	v_div_scale_f32 v223, s[0:1], v221, v221, 1.0
	v_rcp_f32_e32 v251, v223
	s_nop 0
	v_fma_f32 v252, -v223, v251, 1.0
	v_fmac_f32_e32 v251, v252, v251
	v_div_scale_f32 v252, vcc, 1.0, v221, 1.0
	v_mul_f32_e32 v161, v252, v251
	v_fma_f32 v222, -v223, v161, v252
	v_fmac_f32_e32 v161, v222, v251
	v_fma_f32 v223, -v223, v161, v252
	v_div_fmas_f32 v223, v223, v251, v161
	v_div_fixup_f32 v222, v223, v221, 1.0
	v_pk_mul_f32 v[244:245], v[244:245], v[222:223] op_sel_hi:[1,0]
	v_mul_f32_e32 v224, v224, v222
	v_lshlrev_b32_e32 v66, 16, v226
	v_and_b32_e32 v67, 0xffff0000, v226
	v_lshlrev_b32_e32 v68, 16, v146
	v_and_b32_e32 v69, 0xffff0000, v146
	v_lshlrev_b32_e32 v80, 16, v18
	v_and_b32_e32 v81, 0xffff0000, v18
	v_pk_mul_f32 v[66:67], v[244:245], v[66:67] op_sel_hi:[0,1]
	v_pk_fma_f32 v[66:67], v[244:245], v[68:69], v[66:67] op_sel:[1,0,0]
	v_pk_fma_f32 v[66:67], v[224:225], v[80:81], v[66:67] op_sel_hi:[0,1,1]
	v_cvt_pk_bf16_f32 v18, v66, v67
	v_lshlrev_b32_e32 v66, 16, v227
	v_and_b32_e32 v67, 0xffff0000, v227
	v_lshlrev_b32_e32 v68, 16, v147
	v_and_b32_e32 v69, 0xffff0000, v147
	v_lshlrev_b32_e32 v80, 16, v19
	v_and_b32_e32 v81, 0xffff0000, v19
	v_pk_mul_f32 v[66:67], v[244:245], v[66:67] op_sel_hi:[0,1]
	v_pk_fma_f32 v[66:67], v[244:245], v[68:69], v[66:67] op_sel:[1,0,0]
	v_pk_fma_f32 v[66:67], v[224:225], v[80:81], v[66:67] op_sel_hi:[0,1,1]
	v_cvt_pk_bf16_f32 v19, v66, v67
	v_lshlrev_b32_e32 v66, 16, v228
	v_and_b32_e32 v67, 0xffff0000, v228
	v_lshlrev_b32_e32 v68, 16, v148
	v_and_b32_e32 v69, 0xffff0000, v148
	v_lshlrev_b32_e32 v80, 16, v20
	v_and_b32_e32 v81, 0xffff0000, v20
	v_pk_mul_f32 v[66:67], v[244:245], v[66:67] op_sel_hi:[0,1]
	v_pk_fma_f32 v[66:67], v[244:245], v[68:69], v[66:67] op_sel:[1,0,0]
	v_pk_fma_f32 v[66:67], v[224:225], v[80:81], v[66:67] op_sel_hi:[0,1,1]
	v_cvt_pk_bf16_f32 v20, v66, v67
	v_lshlrev_b32_e32 v66, 16, v229
	v_and_b32_e32 v67, 0xffff0000, v229
	v_lshlrev_b32_e32 v68, 16, v149
	v_and_b32_e32 v69, 0xffff0000, v149
	v_lshlrev_b32_e32 v80, 16, v21
	v_and_b32_e32 v81, 0xffff0000, v21
	v_pk_mul_f32 v[66:67], v[244:245], v[66:67] op_sel_hi:[0,1]
	v_pk_fma_f32 v[66:67], v[244:245], v[68:69], v[66:67] op_sel:[1,0,0]
	v_pk_fma_f32 v[66:67], v[224:225], v[80:81], v[66:67] op_sel_hi:[0,1,1]
	v_cvt_pk_bf16_f32 v21, v66, v67
	global_store_dwordx4 v[22:23], v[18:21], off
	v_lshlrev_b32_e32 v66, 16, v230
	v_and_b32_e32 v67, 0xffff0000, v230
	v_lshlrev_b32_e32 v68, 16, v150
	v_and_b32_e32 v69, 0xffff0000, v150
	v_lshlrev_b32_e32 v80, 16, v2
	v_and_b32_e32 v81, 0xffff0000, v2
	v_pk_mul_f32 v[66:67], v[244:245], v[66:67] op_sel_hi:[0,1]
	v_pk_fma_f32 v[66:67], v[244:245], v[68:69], v[66:67] op_sel:[1,0,0]
	v_pk_fma_f32 v[66:67], v[224:225], v[80:81], v[66:67] op_sel_hi:[0,1,1]
; __device__ __forceinline__ unsigned pk2(float lo, float hi) { f32x2_t v = {lo, hi}; bf16x2_t b = __builtin_convertvector(v, bf16x2_t); return __builtin_bit_cast(unsigned, b); }
; __device__ __forceinline__ float bflo(unsigned w) { return __uint_as_float(w << 16); }
; __device__ __forceinline__ float bfhi(unsigned w) { return __uint_as_float(w & 0xffff0000u); }
; __device__ __forceinline__ void phase(LAS unsigned char* L, const u16* __restrict__ QKV, u16* OBg0, u16* OBg1, u16* OBg2, float* LSE, int first, int stride, const int tid) {
;     ...
; #pragma unroll
;         for (int dt = 0; dt < 2; ++dt)
; #pragma unroll
;             for (int gp = 0; gp < 2; ++gp) {
;                 const int ge = 2 * gp, go = 2 * gp + 1;
;                 unsigned e0 = pk2(y[dt][4 * ge] * inv, y[dt][4 * ge + 1] * inv), e1 = pk2(y[dt][4 * ge + 2] * inv, y[dt][4 * ge + 3] * inv);
;                 unsigned o0 = pk2(y[dt][4 * go] * inv, y[dt][4 * go + 1] * inv), o1 = pk2(y[dt][4 * go + 2] * inv, y[dt][4 * go + 3] * inv);
;                 const auto s0 = __builtin_amdgcn_permlane32_swap(e0, o0, false, false); const auto s1 = __builtin_amdgcn_permlane32_swap(e1, o1, false, false);
;                 const v4u wv = {s0[0], s1[0], s0[1], s1[1]};
;                 *(v4u*)(ob + 32 * dt + 8 * (2 * gp + h)) = wv; }
; __device__ __forceinline__ void dil_merge(const u16* OB0, const u16* OB1, const u16* OB2, const float* LSE, u16* MIX, int gw, int NGW, int lane) {
;     ...
;         for (int j = 0; j < 2; ++j) { const v4u a = *(const v4u*)(OB0 + off + 8 * j), bq = *(const v4u*)(OB1 + off + 8 * j), c = *(const v4u*)(OB2 + off + 8 * j);
;             const unsigned aw[4] = {a.x, a.y, a.z, a.w}, bw[4] = {bq.x, bq.y, bq.z, bq.w}, cw[4] = {c.x, c.y, c.z, c.w}; unsigned ow[4];
; #pragma unroll
;             for (int e = 0; e < 4; ++e) ow[e] = pk2(w0 * bflo(aw[e]) + w1 * bflo(bw[e]) + w2 * bflo(cw[e]), w0 * bfhi(aw[e]) + w1 * bfhi(bw[e]) + w2 * bfhi(cw[e]));
;             *(v4u*)(MIX + off + 8 * j) = (v4u){ow[0], ow[1], ow[2], ow[3]}; }
	v_cvt_pk_bf16_f32 v2, v66, v67
	v_lshlrev_b32_e32 v66, 16, v231
	v_and_b32_e32 v67, 0xffff0000, v231
	v_lshlrev_b32_e32 v68, 16, v151
	v_and_b32_e32 v69, 0xffff0000, v151
	v_lshlrev_b32_e32 v80, 16, v3
	v_and_b32_e32 v81, 0xffff0000, v3
	v_pk_mul_f32 v[66:67], v[244:245], v[66:67] op_sel_hi:[0,1]
	v_pk_fma_f32 v[66:67], v[244:245], v[68:69], v[66:67] op_sel:[1,0,0]
	v_pk_fma_f32 v[66:67], v[224:225], v[80:81], v[66:67] op_sel_hi:[0,1,1]
	v_cvt_pk_bf16_f32 v3, v66, v67
	v_lshlrev_b32_e32 v66, 16, v232
	v_and_b32_e32 v67, 0xffff0000, v232
	v_lshlrev_b32_e32 v68, 16, v152
	v_and_b32_e32 v69, 0xffff0000, v152
	v_lshlrev_b32_e32 v80, 16, v4
	v_and_b32_e32 v81, 0xffff0000, v4
	v_pk_mul_f32 v[66:67], v[244:245], v[66:67] op_sel_hi:[0,1]
	v_pk_fma_f32 v[66:67], v[244:245], v[68:69], v[66:67] op_sel:[1,0,0]
	v_pk_fma_f32 v[66:67], v[224:225], v[80:81], v[66:67] op_sel_hi:[0,1,1]
	v_cvt_pk_bf16_f32 v4, v66, v67
	v_lshlrev_b32_e32 v66, 16, v233
	v_and_b32_e32 v67, 0xffff0000, v233
	v_lshlrev_b32_e32 v68, 16, v153
	v_and_b32_e32 v69, 0xffff0000, v153
	v_lshlrev_b32_e32 v80, 16, v5
	v_and_b32_e32 v81, 0xffff0000, v5
	v_pk_mul_f32 v[66:67], v[244:245], v[66:67] op_sel_hi:[0,1]
	v_pk_fma_f32 v[66:67], v[244:245], v[68:69], v[66:67] op_sel:[1,0,0]
	v_pk_fma_f32 v[66:67], v[224:225], v[80:81], v[66:67] op_sel_hi:[0,1,1]
	v_cvt_pk_bf16_f32 v5, v66, v67
	global_store_dwordx4 v[22:23], v[2:5], off offset:64
	v_pk_mul_f32 v[24:25], v[32:33], v[38:39] op_sel_hi:[1,0]
	v_pk_mul_f32 v[18:19], v[26:27], v[38:39] op_sel_hi:[1,0]
	v_pk_mul_f32 v[20:21], v[28:29], v[38:39] op_sel_hi:[1,0]
	v_pk_mul_f32 v[2:3], v[10:11], v[38:39] op_sel_hi:[1,0]
	v_pk_mul_f32 v[4:5], v[12:13], v[38:39] op_sel_hi:[1,0]
	v_cvt_pk_bf16_f32 v18, v18, v19
	v_cvt_pk_bf16_f32 v19, v20, v21
	v_pk_mul_f32 v[20:21], v[30:31], v[38:39] op_sel_hi:[1,0]
	v_cvt_pk_bf16_f32 v2, v2, v3
	v_cvt_pk_bf16_f32 v3, v4, v5
	v_pk_mul_f32 v[4:5], v[14:15], v[38:39] op_sel_hi:[1,0]
	v_pk_mul_f32 v[6:7], v[16:17], v[38:39] op_sel_hi:[1,0]
	v_cvt_pk_bf16_f32 v20, v20, v21
	v_cvt_pk_bf16_f32 v21, v24, v25
	v_cvt_pk_bf16_f32 v4, v4, v5
	v_cvt_pk_bf16_f32 v5, v6, v7
	v_permlane32_swap_b32_e32 v18, v20
	v_permlane32_swap_b32_e32 v19, v21
	v_permlane32_swap_b32_e32 v2, v4
	v_permlane32_swap_b32_e32 v3, v5
	v_lshlrev_b32_e32 v66, 16, v234
	v_and_b32_e32 v67, 0xffff0000, v234
	v_lshlrev_b32_e32 v68, 16, v154
	v_and_b32_e32 v69, 0xffff0000, v154
	v_lshlrev_b32_e32 v80, 16, v18
	v_and_b32_e32 v81, 0xffff0000, v18
	v_pk_mul_f32 v[66:67], v[244:245], v[66:67] op_sel_hi:[0,1]
	v_pk_fma_f32 v[66:67], v[244:245], v[68:69], v[66:67] op_sel:[1,0,0]
	v_pk_fma_f32 v[66:67], v[224:225], v[80:81], v[66:67] op_sel_hi:[0,1,1]
	v_cvt_pk_bf16_f32 v18, v66, v67
	v_lshlrev_b32_e32 v66, 16, v235
	v_and_b32_e32 v67, 0xffff0000, v235
	v_lshlrev_b32_e32 v68, 16, v155
	v_and_b32_e32 v69, 0xffff0000, v155
	v_lshlrev_b32_e32 v80, 16, v19
	v_and_b32_e32 v81, 0xffff0000, v19
	v_pk_mul_f32 v[66:67], v[244:245], v[66:67] op_sel_hi:[0,1]
	v_pk_fma_f32 v[66:67], v[244:245], v[68:69], v[66:67] op_sel:[1,0,0]
	v_pk_fma_f32 v[66:67], v[224:225], v[80:81], v[66:67] op_sel_hi:[0,1,1]
	v_cvt_pk_bf16_f32 v19, v66, v67
	v_lshlrev_b32_e32 v66, 16, v236
	v_and_b32_e32 v67, 0xffff0000, v236
	v_lshlrev_b32_e32 v68, 16, v156
	v_and_b32_e32 v69, 0xffff0000, v156
	v_lshlrev_b32_e32 v80, 16, v20
	v_and_b32_e32 v81, 0xffff0000, v20
	v_pk_mul_f32 v[66:67], v[244:245], v[66:67] op_sel_hi:[0,1]
	v_pk_fma_f32 v[66:67], v[244:245], v[68:69], v[66:67] op_sel:[1,0,0]
	v_pk_fma_f32 v[66:67], v[224:225], v[80:81], v[66:67] op_sel_hi:[0,1,1]
	v_cvt_pk_bf16_f32 v20, v66, v67
	v_lshlrev_b32_e32 v66, 16, v237
	v_and_b32_e32 v67, 0xffff0000, v237
	v_lshlrev_b32_e32 v68, 16, v157
	v_and_b32_e32 v69, 0xffff0000, v157
	v_lshlrev_b32_e32 v80, 16, v21
	v_and_b32_e32 v81, 0xffff0000, v21
	v_pk_mul_f32 v[66:67], v[244:245], v[66:67] op_sel_hi:[0,1]
	v_pk_fma_f32 v[66:67], v[244:245], v[68:69], v[66:67] op_sel:[1,0,0]
	v_pk_fma_f32 v[66:67], v[224:225], v[80:81], v[66:67] op_sel_hi:[0,1,1]
	v_cvt_pk_bf16_f32 v21, v66, v67
	global_store_dwordx4 v[22:23], v[18:21], off offset:32
	v_lshlrev_b32_e32 v66, 16, v238
	v_and_b32_e32 v67, 0xffff0000, v238
	v_lshlrev_b32_e32 v68, 16, v204
	v_and_b32_e32 v69, 0xffff0000, v204
	v_lshlrev_b32_e32 v80, 16, v2
	v_and_b32_e32 v81, 0xffff0000, v2
	v_pk_mul_f32 v[66:67], v[244:245], v[66:67] op_sel_hi:[0,1]
	v_pk_fma_f32 v[66:67], v[244:245], v[68:69], v[66:67] op_sel:[1,0,0]
	v_pk_fma_f32 v[66:67], v[224:225], v[80:81], v[66:67] op_sel_hi:[0,1,1]
	v_cvt_pk_bf16_f32 v2, v66, v67
	v_lshlrev_b32_e32 v66, 16, v239
	v_and_b32_e32 v67, 0xffff0000, v239
	v_lshlrev_b32_e32 v68, 16, v205
	v_and_b32_e32 v69, 0xffff0000, v205
	v_lshlrev_b32_e32 v80, 16, v3
	v_and_b32_e32 v81, 0xffff0000, v3
	v_pk_mul_f32 v[66:67], v[244:245], v[66:67] op_sel_hi:[0,1]
	v_pk_fma_f32 v[66:67], v[244:245], v[68:69], v[66:67] op_sel:[1,0,0]
	v_pk_fma_f32 v[66:67], v[224:225], v[80:81], v[66:67] op_sel_hi:[0,1,1]
	v_cvt_pk_bf16_f32 v3, v66, v67
	v_lshlrev_b32_e32 v66, 16, v240
	v_and_b32_e32 v67, 0xffff0000, v240
	v_lshlrev_b32_e32 v68, 16, v206
	v_and_b32_e32 v69, 0xffff0000, v206
	v_lshlrev_b32_e32 v80, 16, v4
	v_and_b32_e32 v81, 0xffff0000, v4
	v_pk_mul_f32 v[66:67], v[244:245], v[66:67] op_sel_hi:[0,1]
	v_pk_fma_f32 v[66:67], v[244:245], v[68:69], v[66:67] op_sel:[1,0,0]
	v_pk_fma_f32 v[66:67], v[224:225], v[80:81], v[66:67] op_sel_hi:[0,1,1]
	v_cvt_pk_bf16_f32 v4, v66, v67
	v_lshlrev_b32_e32 v66, 16, v241
	v_and_b32_e32 v67, 0xffff0000, v241
	v_lshlrev_b32_e32 v68, 16, v207
	v_and_b32_e32 v69, 0xffff0000, v207
	v_lshlrev_b32_e32 v80, 16, v5
	v_and_b32_e32 v81, 0xffff0000, v5
	v_pk_mul_f32 v[66:67], v[244:245], v[66:67] op_sel_hi:[0,1]
	v_pk_fma_f32 v[66:67], v[244:245], v[68:69], v[66:67] op_sel:[1,0,0]
	v_pk_fma_f32 v[66:67], v[224:225], v[80:81], v[66:67] op_sel_hi:[0,1,1]
	v_cvt_pk_bf16_f32 v5, v66, v67
	global_store_dwordx4 v[22:23], v[2:5], off offset:96
	s_branch .Ldb_latch
; __device__ __forceinline__ int fresh_lane() { int l; asm volatile("v_mbcnt_lo_u32_b32 %0, -1, 0\n\tv_mbcnt_hi_u32_b32 %0, -1, %0" : "=v"(l)); return l; }
; __device__ __forceinline__ unsigned bar_add(unsigned* p) { return __hip_atomic_fetch_add(p, 1u, __ATOMIC_RELAXED, __HIP_MEMORY_SCOPE_AGENT); }
; __device__ __forceinline__ void grid_bar(unsigned* bar, unsigned k, unsigned x, unsigned nloc, unsigned nx, int wave0) {
;     asm volatile("s_waitcnt vmcnt(0) lgkmcnt(0)" ::: "memory");
;     __syncthreads();
;     if (wave0 == 0) {
;         const int ln = fresh_lane();
;         if (ln == 0) {
;             const unsigned old = bar_add(&bar[1024 + 64 * x]);
;             if (old + 1u == k * nloc) {
;                 __builtin_amdgcn_fence(__ATOMIC_RELEASE, "agent");
;                 asm volatile("s_waitcnt vmcnt(0)" ::: "memory");
.Ldb_484:
	v_readlane_b32 s62, v255, 56
	v_readlane_b32 s26, v255, 59
	v_readlane_b32 s28, v255, 61
	v_readlane_b32 s30, v255, 63
	v_readlane_b32 s34, v254, 1
	v_readlane_b32 s58, v254, 14
	v_readlane_b32 s24, v255, 55
	v_readlane_b32 s63, v255, 57
	v_readlane_b32 s57, v255, 58
	v_readlane_b32 s27, v255, 60
	v_readlane_b32 s29, v255, 62
	v_mov_b32_e32 v226, v187
	v_mov_b32_e32 v245, v188
	v_mov_b32_e32 v244, v189
	s_brev_b32 s55, 16
	v_readlane_b32 s31, v254, 0
	v_readlane_b32 s35, v254, 2
	s_mov_b64 s[60:61], 0x150000
	v_readlane_b32 s56, v254, 11
	v_readlane_b32 s59, v254, 15
.LBB0_510:
	s_waitcnt vmcnt(0) lgkmcnt(0)
	v_readlane_b32 s0, v255, 7
	v_readlane_b32 s1, v255, 8
	s_add_i32 s11, s56, 3
	s_and_b64 vcc, exec, s[0:1]
	s_barrier
	s_cbranch_vccz .LBB0_532
	v_mbcnt_lo_u32_b32 v0, -1, 0
	v_mbcnt_hi_u32_b32 v0, -1, v0
	s_nop 0
	v_cmp_eq_u32_e32 vcc, 0, v0
	s_and_saveexec_b64 s[0:1], vcc
	s_cbranch_execz .LBB0_531
	s_mov_b64 s[4:5], exec
	v_mbcnt_lo_u32_b32 v0, s4, 0
	v_mbcnt_hi_u32_b32 v0, s5, v0
	v_cmp_eq_u32_e32 vcc, 0, v0
	s_and_saveexec_b64 s[2:3], vcc
	s_cbranch_execz .LBB0_514
	s_bcnt1_i32_b64 s4, s[4:5]
	v_mov_b32_e32 v2, s4
	v_readlane_b32 s4, v255, 9
	v_readlane_b32 s5, v255, 10
	s_nop 4
	global_atomic_add v2, v1, v2, s[4:5] sc0
